# transposer bf16 stores marked nt so the 160 MB of converted weights do not evict the RWKV operands from the caches during M2
# baseline (speedup 1.0000x reference)
; #define LAS __attribute__((address_space(3)))
; #define GAS __attribute__((address_space(1)))
; __device__ __forceinline__ unsigned pk2(float lo, float hi) { return pg8::cvt_pk_bf16(lo, hi); }
; __device__ __forceinline__ void p0_transpose_item(const GAS float* W, int K, int N, GAS bf16* WT, int mode, LAS float* scr, int item, int lane) {
;     ...
;     const int c = lane & 7;
; #pragma unroll
;     for (int j = 0; j < 4; ++j) { const int n = (lane >> 3) + 8 * j; const LAS float* s = scr + (8 * c) * 33 + n;
;         u32x4 o; o.x = pk2(s[0 * 33], s[1 * 33]); o.y = pk2(s[2 * 33], s[3 * 33]); o.z = pk2(s[4 * 33], s[5 * 33]); o.w = pk2(s[6 * 33], s[7 * 33]);
;         if (mode & 2) __builtin_nontemporal_store(o, (GAS u32x4*)(WT + (size_t)(r0 + n) * K + k0 + 8 * c)); else *(GAS u32x4*)(WT + (size_t)(r0 + n) * K + k0 + 8 * c) = o; }
.Lxp_rd0:
	s_waitcnt lgkmcnt(0)
	ds_read2_b32 v[32:33], v18 offset0:0 offset1:32
	ds_read2_b32 v[34:35], v18 offset0:64 offset1:96
	ds_read2_b32 v[36:37], v18 offset0:128 offset1:160
	ds_read2_b32 v[38:39], v18 offset0:192 offset1:224
	ds_read2_b32 v[40:41], v19 offset0:0 offset1:32
	ds_read2_b32 v[42:43], v19 offset0:64 offset1:96
	ds_read2_b32 v[44:45], v19 offset0:128 offset1:160
	ds_read2_b32 v[46:47], v19 offset0:192 offset1:224
	v_mad_u32_u24 v8, v29, s30, v30
	s_lshl_b32 s31, s30, 4
	s_waitcnt lgkmcnt(4)
	v_cvt_pk_bf16_f32 v32, v32, v33
	v_cvt_pk_bf16_f32 v33, v34, v35
	v_cvt_pk_bf16_f32 v34, v36, v37
	v_cvt_pk_bf16_f32 v35, v38, v39
	global_store_dwordx4 v8, v[32:35], s[44:45] nt
	v_add_u32_e32 v8, s31, v8
	s_waitcnt lgkmcnt(0)
	v_cvt_pk_bf16_f32 v40, v40, v41
	v_cvt_pk_bf16_f32 v41, v42, v43
	v_cvt_pk_bf16_f32 v42, v44, v45
	v_cvt_pk_bf16_f32 v43, v46, v47
	global_store_dwordx4 v8, v[40:43], s[44:45] nt
	s_branch .Lxp_ret

; #define LAS __attribute__((address_space(3)))
; #define GAS __attribute__((address_space(1)))
; __device__ __forceinline__ unsigned pk2(float lo, float hi) { return pg8::cvt_pk_bf16(lo, hi); }
; #define LDS_WAIT() asm volatile("s_waitcnt lgkmcnt(0)" ::: "memory")
; __device__ __forceinline__ void p0_transpose_item(const GAS float* W, int K, int N, GAS bf16* WT, int mode, LAS float* scr, int item, int lane) {
;     ...
;     const int c = lane & 7;
; #pragma unroll
;     for (int j = 0; j < 4; ++j) { const int n = (lane >> 3) + 8 * j; const LAS float* s = scr + (8 * c) * 33 + n;
;         u32x4 o; o.x = pk2(s[0 * 33], s[1 * 33]); o.y = pk2(s[2 * 33], s[3 * 33]); o.z = pk2(s[4 * 33], s[5 * 33]); o.w = pk2(s[6 * 33], s[7 * 33]);
;         if (mode & 2) __builtin_nontemporal_store(o, (GAS u32x4*)(WT + (size_t)(r0 + n) * K + k0 + 8 * c)); else *(GAS u32x4*)(WT + (size_t)(r0 + n) * K + k0 + 8 * c) = o; }
;     LDS_WAIT();
.Lxp_ret:
	s_add_u32 s23, s23, 1
	s_cmp_eq_u32 s23, 3
	s_cselect_b32 s23, 0, s23
	s_add_u32 s18, s18, 1
	s_cmp_le_u32 s18, 0x80
	s_cbranch_scc1 .Lld_loop
	s_waitcnt vmcnt(0)
	s_movk_i32 s19, 125
	s_cmp_ge_u32 s19, s12
	s_cbranch_scc1 .Lxp_dr125
	s_sub_u32 s19, s19, 64
	v_readlane_b32 s44, v104, s19
	v_readlane_b32 s45, v105, s19
	v_readlane_b32 s30, v107, s19
	ds_write_b128 v11, v[80:83] offset:0
	ds_write_b128 v12, v[84:87] offset:1024
	ds_write_b128 v13, v[88:91] offset:2048
	ds_write_b128 v14, v[92:95] offset:3072
	s_waitcnt lgkmcnt(0)
	ds_read2_b32 v[32:33], v18 offset0:0 offset1:32
	ds_read2_b32 v[34:35], v18 offset0:64 offset1:96
	ds_read2_b32 v[36:37], v18 offset0:128 offset1:160
	ds_read2_b32 v[38:39], v18 offset0:192 offset1:224
	ds_read2_b32 v[40:41], v19 offset0:0 offset1:32
	ds_read2_b32 v[42:43], v19 offset0:64 offset1:96
	ds_read2_b32 v[44:45], v19 offset0:128 offset1:160
	ds_read2_b32 v[46:47], v19 offset0:192 offset1:224
	v_mad_u32_u24 v8, v29, s30, v30
	s_lshl_b32 s31, s30, 4
	s_waitcnt lgkmcnt(4)
	v_cvt_pk_bf16_f32 v32, v32, v33
	v_cvt_pk_bf16_f32 v33, v34, v35
	v_cvt_pk_bf16_f32 v34, v36, v37
	v_cvt_pk_bf16_f32 v35, v38, v39
	global_store_dwordx4 v8, v[32:35], s[44:45] nt
	v_add_u32_e32 v8, s31, v8
	s_waitcnt lgkmcnt(0)
	v_cvt_pk_bf16_f32 v40, v40, v41
	v_cvt_pk_bf16_f32 v41, v42, v43
	v_cvt_pk_bf16_f32 v42, v44, v45
	v_cvt_pk_bf16_f32 v43, v46, v47
	global_store_dwordx4 v8, v[40:43], s[44:45] nt
	s_nop 1
.Lxp_dr125:
	s_movk_i32 s19, 126
	s_cmp_ge_u32 s19, s12
	s_cbranch_scc1 .Lxp_dr126
	s_sub_u32 s19, s19, 64
	v_readlane_b32 s44, v104, s19
	v_readlane_b32 s45, v105, s19
	v_readlane_b32 s30, v107, s19
	ds_write_b128 v11, v[48:51] offset:0
	ds_write_b128 v12, v[52:55] offset:1024
	ds_write_b128 v13, v[56:59] offset:2048
	ds_write_b128 v14, v[60:63] offset:3072
	s_waitcnt lgkmcnt(0)
	ds_read2_b32 v[32:33], v18 offset0:0 offset1:32
	ds_read2_b32 v[34:35], v18 offset0:64 offset1:96
	ds_read2_b32 v[36:37], v18 offset0:128 offset1:160
	ds_read2_b32 v[38:39], v18 offset0:192 offset1:224
	ds_read2_b32 v[40:41], v19 offset0:0 offset1:32
	ds_read2_b32 v[42:43], v19 offset0:64 offset1:96
	ds_read2_b32 v[44:45], v19 offset0:128 offset1:160
	ds_read2_b32 v[46:47], v19 offset0:192 offset1:224
	v_mad_u32_u24 v8, v29, s30, v30
	s_lshl_b32 s31, s30, 4
	s_waitcnt lgkmcnt(4)
	v_cvt_pk_bf16_f32 v32, v32, v33
	v_cvt_pk_bf16_f32 v33, v34, v35
	v_cvt_pk_bf16_f32 v34, v36, v37
	v_cvt_pk_bf16_f32 v35, v38, v39
	global_store_dwordx4 v8, v[32:35], s[44:45] nt
	v_add_u32_e32 v8, s31, v8
	s_waitcnt lgkmcnt(0)
	v_cvt_pk_bf16_f32 v40, v40, v41
	v_cvt_pk_bf16_f32 v41, v42, v43
	v_cvt_pk_bf16_f32 v42, v44, v45
	v_cvt_pk_bf16_f32 v43, v46, v47
	global_store_dwordx4 v8, v[40:43], s[44:45] nt
	s_nop 1
.Lxp_dr126:
	s_movk_i32 s19, 127
	s_cmp_ge_u32 s19, s12
	s_cbranch_scc1 .Lxp_dr127
	s_sub_u32 s19, s19, 64
	v_readlane_b32 s44, v104, s19
	v_readlane_b32 s45, v105, s19
	v_readlane_b32 s30, v107, s19
	ds_write_b128 v11, v[64:67] offset:0
	ds_write_b128 v12, v[68:71] offset:1024
	ds_write_b128 v13, v[72:75] offset:2048
	ds_write_b128 v14, v[76:79] offset:3072
	s_waitcnt lgkmcnt(0)
	ds_read2_b32 v[32:33], v18 offset0:0 offset1:32
	ds_read2_b32 v[34:35], v18 offset0:64 offset1:96
	ds_read2_b32 v[36:37], v18 offset0:128 offset1:160
	ds_read2_b32 v[38:39], v18 offset0:192 offset1:224
	ds_read2_b32 v[40:41], v19 offset0:0 offset1:32
	ds_read2_b32 v[42:43], v19 offset0:64 offset1:96
	ds_read2_b32 v[44:45], v19 offset0:128 offset1:160
	ds_read2_b32 v[46:47], v19 offset0:192 offset1:224
	v_mad_u32_u24 v8, v29, s30, v30
	s_lshl_b32 s31, s30, 4
	s_waitcnt lgkmcnt(4)
	v_cvt_pk_bf16_f32 v32, v32, v33
	v_cvt_pk_bf16_f32 v33, v34, v35
	v_cvt_pk_bf16_f32 v34, v36, v37
	v_cvt_pk_bf16_f32 v35, v38, v39
	global_store_dwordx4 v8, v[32:35], s[44:45] nt
	v_add_u32_e32 v8, s31, v8
	s_waitcnt lgkmcnt(0)
	v_cvt_pk_bf16_f32 v40, v40, v41
	v_cvt_pk_bf16_f32 v41, v42, v43
	v_cvt_pk_bf16_f32 v42, v44, v45
	v_cvt_pk_bf16_f32 v43, v46, v47
	global_store_dwordx4 v8, v[40:43], s[44:45] nt
	s_nop 1
